# v2 + P1 cache_k/cache_v row conversion: eight loads issued together instead of four dependent load-convert-store round trips
# baseline (speedup 1.0000x reference)
.LBB0_89:
	s_cmpk_gt_i32 s0, 0x3ff
	s_mov_b64 s[2:3], -1
	s_cbranch_scc0 .LBB0_91
	s_add_i32 s6, s0, 0xfffffc00
	v_readlane_b32 s52, v249, 9
	s_lshl_b64 s[2:3], s[6:7], 13
	v_readlane_b32 s58, v249, 15
	v_readlane_b32 s59, v249, 16
	s_add_u32 s2, s58, s2
	s_addc_u32 s3, s59, s3
	global_load_dwordx4 v[2:5], v1, s[2:3]
	global_load_dwordx4 v[10:13], v1, s[2:3] offset:16
	global_load_dwordx4 v[14:17], v1, s[2:3] offset:2048
	global_load_dwordx4 v[18:21], v1, s[2:3] offset:2064
	global_load_dwordx4 v[22:25], v7, s[2:3]
	global_load_dwordx4 v[26:29], v7, s[2:3] offset:16
	global_load_dwordx4 v[30:33], v8, s[2:3]
	global_load_dwordx4 v[34:37], v8, s[2:3] offset:16
	s_lshl_b64 s[4:5], s[6:7], 12
	s_add_u32 s4, s71, s4
	v_readlane_b32 s1, v249, 49
	s_addc_u32 s5, s1, s5
	v_readlane_b32 s53, v249, 10
	v_readlane_b32 s54, v249, 11
	v_readlane_b32 s55, v249, 12
	v_readlane_b32 s56, v249, 13
	v_readlane_b32 s57, v249, 14
	v_readlane_b32 s60, v249, 17
	v_readlane_b32 s61, v249, 18
	v_readlane_b32 s62, v249, 19
	v_readlane_b32 s63, v249, 20
	v_readlane_b32 s64, v249, 21
	v_readlane_b32 s65, v249, 22
	v_readlane_b32 s66, v249, 23
	v_readlane_b32 s67, v249, 24
	s_waitcnt vmcnt(6)
	v_cvt_pk_bf16_f32 v2, v2, v3
	v_cvt_pk_bf16_f32 v3, v4, v5
	v_cvt_pk_bf16_f32 v4, v10, v11
	v_cvt_pk_bf16_f32 v5, v12, v13
	global_store_dwordx4 v6, v[2:5], s[4:5]
	s_waitcnt vmcnt(5)
	v_cvt_pk_bf16_f32 v14, v14, v15
	v_cvt_pk_bf16_f32 v15, v16, v17
	v_cvt_pk_bf16_f32 v16, v18, v19
	v_cvt_pk_bf16_f32 v17, v20, v21
	global_store_dwordx4 v6, v[14:17], s[4:5] offset:1024
	s_waitcnt vmcnt(4)
	v_cvt_pk_bf16_f32 v22, v22, v23
	v_cvt_pk_bf16_f32 v23, v24, v25
	v_cvt_pk_bf16_f32 v24, v26, v27
	v_cvt_pk_bf16_f32 v25, v28, v29
	global_store_dwordx4 v6, v[22:25], s[4:5] offset:2048
	s_waitcnt vmcnt(3)
	v_cvt_pk_bf16_f32 v2, v30, v31
	v_cvt_pk_bf16_f32 v3, v32, v33
	v_cvt_pk_bf16_f32 v4, v34, v35
	v_cvt_pk_bf16_f32 v5, v36, v37
	s_cbranch_execnz .LBB0_88
	s_branch .LBB0_92

.LBB0_92:
	s_ashr_i32 s1, s0, 31
	s_lshr_b32 s2, s1, 24
	v_readlane_b32 s52, v249, 9
	s_add_i32 s4, s0, s2
	s_lshl_b64 s[2:3], s[0:1], 13
	v_readlane_b32 s56, v249, 13
	v_readlane_b32 s57, v249, 14
	s_add_u32 s2, s56, s2
	s_addc_u32 s3, s57, s3
	global_load_dwordx4 v[2:5], v1, s[2:3]
	global_load_dwordx4 v[10:13], v1, s[2:3] offset:16
	global_load_dwordx4 v[14:17], v1, s[2:3] offset:2048
	global_load_dwordx4 v[18:21], v1, s[2:3] offset:2064
	global_load_dwordx4 v[22:25], v7, s[2:3]
	global_load_dwordx4 v[26:29], v7, s[2:3] offset:16
	global_load_dwordx4 v[30:33], v8, s[2:3]
	global_load_dwordx4 v[34:37], v8, s[2:3] offset:16
	s_lshl_b32 s1, s4, 2
	s_and_b32 s1, s1, 0xfffffc00
	s_add_i32 s1, s0, s1
	s_add_i32 s4, s1, 0x2400
	s_ashr_i32 s5, s4, 31
	s_lshl_b64 s[4:5], s[4:5], 12
	v_readlane_b32 s8, v249, 47
	v_readlane_b32 s9, v249, 48
	s_add_u32 s4, s8, s4
	s_addc_u32 s5, s9, s5
	v_readlane_b32 s53, v249, 10
	v_readlane_b32 s54, v249, 11
	v_readlane_b32 s55, v249, 12
	v_readlane_b32 s58, v249, 15
	v_readlane_b32 s59, v249, 16
	v_readlane_b32 s60, v249, 17
	v_readlane_b32 s61, v249, 18
	v_readlane_b32 s62, v249, 19
	v_readlane_b32 s63, v249, 20
	v_readlane_b32 s64, v249, 21
	v_readlane_b32 s65, v249, 22
	v_readlane_b32 s66, v249, 23
	v_readlane_b32 s67, v249, 24
	s_waitcnt vmcnt(6)
	v_cvt_pk_bf16_f32 v2, v2, v3
	v_cvt_pk_bf16_f32 v3, v4, v5
	v_cvt_pk_bf16_f32 v4, v10, v11
	v_cvt_pk_bf16_f32 v5, v12, v13
	global_store_dwordx4 v6, v[2:5], s[4:5]
	s_waitcnt vmcnt(5)
	v_cvt_pk_bf16_f32 v14, v14, v15
	v_cvt_pk_bf16_f32 v15, v16, v17
	v_cvt_pk_bf16_f32 v16, v18, v19
	v_cvt_pk_bf16_f32 v17, v20, v21
	global_store_dwordx4 v6, v[14:17], s[4:5] offset:1024
	s_waitcnt vmcnt(4)
	v_cvt_pk_bf16_f32 v22, v22, v23
	v_cvt_pk_bf16_f32 v23, v24, v25
	v_cvt_pk_bf16_f32 v24, v26, v27
	v_cvt_pk_bf16_f32 v25, v28, v29
	global_store_dwordx4 v6, v[22:25], s[4:5] offset:2048
	s_waitcnt vmcnt(3)
	v_cvt_pk_bf16_f32 v2, v30, v31
	v_cvt_pk_bf16_f32 v3, v32, v33
	v_cvt_pk_bf16_f32 v4, v34, v35
	v_cvt_pk_bf16_f32 v5, v36, v37
	s_branch .LBB0_88
